# GEMM silu epilogues (phases 2, 6): scale and +1 as packed f32 ops
# speedup vs baseline: 1.0129x; 1.0020x over previous
.LBB0_242:
	ds_read_b128 v[152:155], v149
	ds_read_b128 v[156:159], v149 offset:1024
	ds_read_b128 v[160:163], v149 offset:2048
	ds_read_b128 v[164:167], v149 offset:3072
	s_add_u32 s66, s6, 0xfffc0080
	s_addc_u32 s67, s7, -1
	s_cmp_eq_u32 s95, 12
	s_cselect_b32 s75, s25, s67
	s_cselect_b32 s74, s90, s66
	s_cselect_b32 s67, s13, s93
	s_cselect_b32 s66, s91, s92
	v_lshl_add_u64 v[146:147], s[6:7], 0, v[138:139]
	s_add_i32 m0, s61, 0xc000
	ds_read_b128 v[168:171], v150
	ds_read_b128 v[172:175], v150 offset:1024
	ds_read_b128 v[176:179], v150 offset:2048
	ds_read_b128 v[180:183], v150 offset:3072
	ds_read_b128 v[192:195], v150 offset:4096
	ds_read_b128 v[196:199], v150 offset:5120
	ds_read_b128 v[200:203], v150 offset:6144
	ds_read_b128 v[204:207], v150 offset:7168
	global_load_lds_dwordx4 v[146:147], off
	v_lshl_add_u64 v[146:147], s[6:7], 0, v[140:141]
	s_add_i32 m0, s61, 0xe000
	s_nop 0
	global_load_lds_dwordx4 v[146:147], off
	s_waitcnt lgkmcnt(8)
	s_barrier
	s_waitcnt lgkmcnt(0)
	s_setprio 1
	s_waitcnt lgkmcnt(0)
	v_mfma_f32_16x16x32_bf16 v[124:127], v[152:155], v[168:171], v[124:127]
	v_mfma_f32_16x16x32_bf16 v[120:123], v[160:163], v[168:171], v[120:123]
	v_mfma_f32_16x16x32_bf16 v[108:111], v[152:155], v[176:179], v[108:111]
	v_mfma_f32_16x16x32_bf16 v[104:107], v[160:163], v[176:179], v[104:107]
	v_mfma_f32_16x16x32_bf16 v[92:95], v[152:155], v[192:195], v[92:95]
	v_mfma_f32_16x16x32_bf16 v[88:91], v[160:163], v[192:195], v[88:91]
	v_mfma_f32_16x16x32_bf16 v[76:79], v[152:155], v[200:203], v[76:79]
	v_mfma_f32_16x16x32_bf16 v[72:75], v[160:163], v[200:203], v[72:75]
	v_mfma_f32_16x16x32_bf16 v[124:127], v[156:159], v[172:175], v[124:127]
	v_mfma_f32_16x16x32_bf16 v[120:123], v[164:167], v[172:175], v[120:123]
	v_mfma_f32_16x16x32_bf16 v[108:111], v[156:159], v[180:183], v[108:111]
	v_mfma_f32_16x16x32_bf16 v[104:107], v[164:167], v[180:183], v[104:107]
	v_mfma_f32_16x16x32_bf16 v[92:95], v[156:159], v[196:199], v[92:95]
	v_mfma_f32_16x16x32_bf16 v[88:91], v[164:167], v[196:199], v[88:91]
	v_mfma_f32_16x16x32_bf16 v[76:79], v[156:159], v[204:207], v[76:79]
	v_mfma_f32_16x16x32_bf16 v[72:75], v[164:167], v[204:207], v[72:75]
	s_setprio 0
	s_barrier
	s_add_i32 s96, s86, s76
	v_lshl_add_u64 v[146:147], s[66:67], 0, v[130:131]
	s_mov_b32 m0, s96
	ds_read_b128 v[208:211], v151
	ds_read_b128 v[212:215], v151 offset:1024
	ds_read_b128 v[216:219], v151 offset:2048
	ds_read_b128 v[220:223], v151 offset:3072
	global_load_lds_dwordx4 v[146:147], off
	v_lshl_add_u64 v[184:185], s[66:67], 0, v[134:135]
	s_add_i32 m0, s96, 0x2000
	s_nop 0
	global_load_lds_dwordx4 v[184:185], off
	s_barrier
	s_waitcnt lgkmcnt(0)
	s_setprio 1
	s_waitcnt lgkmcnt(0)
	v_mfma_f32_16x16x32_bf16 v[116:119], v[208:211], v[168:171], v[116:119]
	v_mfma_f32_16x16x32_bf16 v[112:115], v[216:219], v[168:171], v[112:115]
	v_mfma_f32_16x16x32_bf16 v[100:103], v[208:211], v[176:179], v[100:103]
	v_mfma_f32_16x16x32_bf16 v[96:99], v[216:219], v[176:179], v[96:99]
	v_mfma_f32_16x16x32_bf16 v[84:87], v[208:211], v[192:195], v[84:87]
	v_mfma_f32_16x16x32_bf16 v[80:83], v[216:219], v[192:195], v[80:83]
	v_mfma_f32_16x16x32_bf16 v[68:71], v[208:211], v[200:203], v[68:71]
	v_mfma_f32_16x16x32_bf16 v[64:67], v[216:219], v[200:203], v[64:67]
	v_mfma_f32_16x16x32_bf16 v[116:119], v[212:215], v[172:175], v[116:119]
	v_mfma_f32_16x16x32_bf16 v[112:115], v[220:223], v[172:175], v[112:115]
	v_mfma_f32_16x16x32_bf16 v[100:103], v[212:215], v[180:183], v[100:103]
	v_mfma_f32_16x16x32_bf16 v[96:99], v[220:223], v[180:183], v[96:99]
	v_mfma_f32_16x16x32_bf16 v[84:87], v[212:215], v[196:199], v[84:87]
	v_mfma_f32_16x16x32_bf16 v[80:83], v[220:223], v[196:199], v[80:83]
	v_mfma_f32_16x16x32_bf16 v[68:71], v[212:215], v[204:207], v[68:71]
	v_mfma_f32_16x16x32_bf16 v[64:67], v[220:223], v[204:207], v[64:67]
	s_setprio 0
	s_mov_b32 m0, s61
	v_lshl_add_u64 v[188:189], s[74:75], 0, v[128:129]
	s_barrier
	ds_read_b128 v[168:171], v150 offset:16384
	ds_read_b128 v[172:175], v150 offset:17408
	ds_read_b128 v[176:179], v150 offset:18432
	ds_read_b128 v[180:183], v150 offset:19456
	ds_read_b128 v[192:195], v150 offset:20480
	ds_read_b128 v[196:199], v150 offset:21504
	ds_read_b128 v[200:203], v150 offset:22528
	ds_read_b128 v[204:207], v150 offset:23552
	global_load_lds_dwordx4 v[188:189], off
	v_lshl_add_u64 v[224:225], s[74:75], 0, v[132:133]
	s_mov_b32 m0, s77
	s_nop 0
	global_load_lds_dwordx4 v[224:225], off
	s_barrier
	s_waitcnt lgkmcnt(0)
	s_setprio 1
	s_waitcnt lgkmcnt(0)
	v_mfma_f32_16x16x32_bf16 v[60:63], v[152:155], v[168:171], v[60:63]
	v_mfma_f32_16x16x32_bf16 v[56:59], v[160:163], v[168:171], v[56:59]
	v_mfma_f32_16x16x32_bf16 v[44:47], v[152:155], v[176:179], v[44:47]
	v_mfma_f32_16x16x32_bf16 v[40:43], v[160:163], v[176:179], v[40:43]
	v_mfma_f32_16x16x32_bf16 v[28:31], v[152:155], v[192:195], v[28:31]
	v_mfma_f32_16x16x32_bf16 v[24:27], v[160:163], v[192:195], v[24:27]
	v_mfma_f32_16x16x32_bf16 v[12:15], v[152:155], v[200:203], v[12:15]
	v_mfma_f32_16x16x32_bf16 v[8:11], v[160:163], v[200:203], v[8:11]
	v_mfma_f32_16x16x32_bf16 v[60:63], v[156:159], v[172:175], v[60:63]
	v_mfma_f32_16x16x32_bf16 v[56:59], v[164:167], v[172:175], v[56:59]
	v_mfma_f32_16x16x32_bf16 v[44:47], v[156:159], v[180:183], v[44:47]
	v_mfma_f32_16x16x32_bf16 v[40:43], v[164:167], v[180:183], v[40:43]
	v_mfma_f32_16x16x32_bf16 v[28:31], v[156:159], v[196:199], v[28:31]
	v_mfma_f32_16x16x32_bf16 v[24:27], v[164:167], v[196:199], v[24:27]
	v_mfma_f32_16x16x32_bf16 v[12:15], v[156:159], v[204:207], v[12:15]
	v_mfma_f32_16x16x32_bf16 v[8:11], v[164:167], v[204:207], v[8:11]
	s_setprio 0
	s_barrier
	s_add_u32 s96, s66, 0x40000
	s_addc_u32 s97, s67, 0
	s_add_i32 vcc_lo, s87, s76
	v_lshl_add_u64 v[152:153], s[96:97], 0, v[130:131]
	s_mov_b32 m0, vcc_lo
	s_nop 0
	global_load_lds_dwordx4 v[152:153], off
	v_lshl_add_u64 v[152:153], s[96:97], 0, v[134:135]
	s_add_i32 m0, vcc_lo, 0x2000
	s_nop 0
	global_load_lds_dwordx4 v[152:153], off
	s_waitcnt vmcnt(6)
	s_barrier
	s_setprio 1
	v_mfma_f32_16x16x32_bf16 v[52:55], v[208:211], v[168:171], v[52:55]
	v_mfma_f32_16x16x32_bf16 v[48:51], v[216:219], v[168:171], v[48:51]
	v_mfma_f32_16x16x32_bf16 v[36:39], v[208:211], v[176:179], v[36:39]
	v_mfma_f32_16x16x32_bf16 v[32:35], v[216:219], v[176:179], v[32:35]
	v_mfma_f32_16x16x32_bf16 v[20:23], v[208:211], v[192:195], v[20:23]
	v_mfma_f32_16x16x32_bf16 v[16:19], v[216:219], v[192:195], v[16:19]
	v_mfma_f32_16x16x32_bf16 v[4:7], v[208:211], v[200:203], v[4:7]
	v_mfma_f32_16x16x32_bf16 v[0:3], v[216:219], v[200:203], v[0:3]
	v_mfma_f32_16x16x32_bf16 v[52:55], v[212:215], v[172:175], v[52:55]
	v_mfma_f32_16x16x32_bf16 v[48:51], v[220:223], v[172:175], v[48:51]
	v_mfma_f32_16x16x32_bf16 v[36:39], v[212:215], v[180:183], v[36:39]
	v_mfma_f32_16x16x32_bf16 v[32:35], v[220:223], v[180:183], v[32:35]
	v_mfma_f32_16x16x32_bf16 v[20:23], v[212:215], v[196:199], v[20:23]
	v_mfma_f32_16x16x32_bf16 v[16:19], v[220:223], v[196:199], v[16:19]
	v_mfma_f32_16x16x32_bf16 v[4:7], v[212:215], v[204:207], v[4:7]
	v_mfma_f32_16x16x32_bf16 v[0:3], v[220:223], v[204:207], v[0:3]
	s_setprio 0
	s_add_i32 s96, 0, 0x18000
	v_add_u32_e32 v136, s96, v148
	s_barrier
	ds_read_b128 v[152:155], v136
	ds_read_b128 v[156:159], v136 offset:1024
	ds_read_b128 v[160:163], v136 offset:2048
	ds_read_b128 v[164:167], v136 offset:3072
	s_add_u32 s74, s74, 0x40000
	s_addc_u32 s75, s75, 0
	s_mov_b32 m0, s78
	v_lshl_add_u64 v[208:209], s[74:75], 0, v[128:129]
	ds_read_b128 v[168:171], v150 offset:32768
	ds_read_b128 v[172:175], v150 offset:33792
	ds_read_b128 v[176:179], v150 offset:34816
	ds_read_b128 v[180:183], v150 offset:35840
	ds_read_b128 v[192:195], v150 offset:36864
	ds_read_b128 v[196:199], v150 offset:37888
	ds_read_b128 v[200:203], v150 offset:38912
	ds_read_b128 v[204:207], v150 offset:39936
	global_load_lds_dwordx4 v[208:209], off
	v_lshl_add_u64 v[208:209], s[74:75], 0, v[132:133]
	s_mov_b32 m0, s79
	s_nop 0
	global_load_lds_dwordx4 v[208:209], off
	s_waitcnt lgkmcnt(8)
	s_barrier
	s_waitcnt lgkmcnt(0)
	s_setprio 1
	s_waitcnt lgkmcnt(0)
	v_mfma_f32_16x16x32_bf16 v[124:127], v[152:155], v[168:171], v[124:127]
	v_mfma_f32_16x16x32_bf16 v[120:123], v[160:163], v[168:171], v[120:123]
	v_mfma_f32_16x16x32_bf16 v[108:111], v[152:155], v[176:179], v[108:111]
	v_mfma_f32_16x16x32_bf16 v[104:107], v[160:163], v[176:179], v[104:107]
	v_mfma_f32_16x16x32_bf16 v[92:95], v[152:155], v[192:195], v[92:95]
	v_mfma_f32_16x16x32_bf16 v[88:91], v[160:163], v[192:195], v[88:91]
	v_mfma_f32_16x16x32_bf16 v[76:79], v[152:155], v[200:203], v[76:79]
	v_mfma_f32_16x16x32_bf16 v[72:75], v[160:163], v[200:203], v[72:75]
	v_mfma_f32_16x16x32_bf16 v[124:127], v[156:159], v[172:175], v[124:127]
	v_mfma_f32_16x16x32_bf16 v[120:123], v[164:167], v[172:175], v[120:123]
	v_mfma_f32_16x16x32_bf16 v[108:111], v[156:159], v[180:183], v[108:111]
	v_mfma_f32_16x16x32_bf16 v[104:107], v[164:167], v[180:183], v[104:107]
	v_mfma_f32_16x16x32_bf16 v[92:95], v[156:159], v[196:199], v[92:95]
	v_mfma_f32_16x16x32_bf16 v[88:91], v[164:167], v[196:199], v[88:91]
	v_mfma_f32_16x16x32_bf16 v[76:79], v[156:159], v[204:207], v[76:79]
	v_mfma_f32_16x16x32_bf16 v[72:75], v[164:167], v[204:207], v[72:75]
	s_setprio 0
	s_barrier
	s_add_i32 s74, 0, 0x1c000
	s_add_i32 s75, s96, s76
	v_add_u32_e32 v136, s74, v148
	v_lshl_add_u64 v[146:147], v[146:147], 0, s[8:9]
	s_mov_b32 m0, s75
	ds_read_b128 v[208:211], v136
	ds_read_b128 v[212:215], v136 offset:1024
	ds_read_b128 v[216:219], v136 offset:2048
	ds_read_b128 v[220:223], v136 offset:3072
	global_load_lds_dwordx4 v[146:147], off
	v_lshl_add_u64 v[146:147], v[184:185], 0, s[8:9]
	s_add_i32 m0, s75, 0x2000
	s_nop 0
	global_load_lds_dwordx4 v[146:147], off
	s_barrier
	s_waitcnt lgkmcnt(0)
	s_setprio 1
	s_waitcnt lgkmcnt(0)
	v_mfma_f32_16x16x32_bf16 v[116:119], v[208:211], v[168:171], v[116:119]
	v_mfma_f32_16x16x32_bf16 v[112:115], v[216:219], v[168:171], v[112:115]
	v_mfma_f32_16x16x32_bf16 v[100:103], v[208:211], v[176:179], v[100:103]
	v_mfma_f32_16x16x32_bf16 v[96:99], v[216:219], v[176:179], v[96:99]
	v_mfma_f32_16x16x32_bf16 v[84:87], v[208:211], v[192:195], v[84:87]
	v_mfma_f32_16x16x32_bf16 v[80:83], v[216:219], v[192:195], v[80:83]
	v_mfma_f32_16x16x32_bf16 v[68:71], v[208:211], v[200:203], v[68:71]
	v_mfma_f32_16x16x32_bf16 v[64:67], v[216:219], v[200:203], v[64:67]
	v_mfma_f32_16x16x32_bf16 v[116:119], v[212:215], v[172:175], v[116:119]
	v_mfma_f32_16x16x32_bf16 v[112:115], v[220:223], v[172:175], v[112:115]
	v_mfma_f32_16x16x32_bf16 v[100:103], v[212:215], v[180:183], v[100:103]
	v_mfma_f32_16x16x32_bf16 v[96:99], v[220:223], v[180:183], v[96:99]
	v_mfma_f32_16x16x32_bf16 v[84:87], v[212:215], v[196:199], v[84:87]
	v_mfma_f32_16x16x32_bf16 v[80:83], v[220:223], v[196:199], v[80:83]
	v_mfma_f32_16x16x32_bf16 v[68:71], v[212:215], v[204:207], v[68:71]
	v_mfma_f32_16x16x32_bf16 v[64:67], v[220:223], v[204:207], v[64:67]
	s_setprio 0
	s_mov_b32 m0, s80
	v_lshl_add_u64 v[146:147], v[188:189], 0, s[8:9]
	s_barrier
	ds_read_b128 v[168:171], v150 offset:49152
	ds_read_b128 v[172:175], v150 offset:50176
	ds_read_b128 v[176:179], v150 offset:51200
	ds_read_b128 v[180:183], v150 offset:52224
	ds_read_b128 v[192:195], v150 offset:53248
	ds_read_b128 v[196:199], v150 offset:54272
	ds_read_b128 v[200:203], v150 offset:55296
	ds_read_b128 v[204:207], v150 offset:56320
	global_load_lds_dwordx4 v[146:147], off
	v_lshl_add_u64 v[146:147], v[224:225], 0, s[8:9]
	s_mov_b32 m0, s81
	s_nop 0
	global_load_lds_dwordx4 v[146:147], off
	s_barrier
	s_waitcnt lgkmcnt(0)
	s_setprio 1
	s_waitcnt lgkmcnt(0)
	v_mfma_f32_16x16x32_bf16 v[60:63], v[152:155], v[168:171], v[60:63]
	v_mfma_f32_16x16x32_bf16 v[56:59], v[160:163], v[168:171], v[56:59]
	v_mfma_f32_16x16x32_bf16 v[44:47], v[152:155], v[176:179], v[44:47]
	v_mfma_f32_16x16x32_bf16 v[40:43], v[160:163], v[176:179], v[40:43]
	v_mfma_f32_16x16x32_bf16 v[28:31], v[152:155], v[192:195], v[28:31]
	v_mfma_f32_16x16x32_bf16 v[24:27], v[160:163], v[192:195], v[24:27]
	v_mfma_f32_16x16x32_bf16 v[12:15], v[152:155], v[200:203], v[12:15]
	v_mfma_f32_16x16x32_bf16 v[8:11], v[160:163], v[200:203], v[8:11]
	v_mfma_f32_16x16x32_bf16 v[60:63], v[156:159], v[172:175], v[60:63]
	v_mfma_f32_16x16x32_bf16 v[56:59], v[164:167], v[172:175], v[56:59]
	v_mfma_f32_16x16x32_bf16 v[44:47], v[156:159], v[180:183], v[44:47]
	v_mfma_f32_16x16x32_bf16 v[40:43], v[164:167], v[180:183], v[40:43]
	v_mfma_f32_16x16x32_bf16 v[28:31], v[156:159], v[196:199], v[28:31]
	v_mfma_f32_16x16x32_bf16 v[24:27], v[164:167], v[196:199], v[24:27]
	v_mfma_f32_16x16x32_bf16 v[12:15], v[156:159], v[204:207], v[12:15]
	v_mfma_f32_16x16x32_bf16 v[8:11], v[164:167], v[204:207], v[8:11]
	s_setprio 0
	s_barrier
	s_add_u32 s66, s66, 0x40080
	s_addc_u32 s67, s67, 0
	s_add_i32 s74, s74, s76
	v_lshl_add_u64 v[146:147], s[66:67], 0, v[130:131]
	s_mov_b32 m0, s74
	s_nop 0
	global_load_lds_dwordx4 v[146:147], off
	v_lshl_add_u64 v[146:147], s[66:67], 0, v[134:135]
	s_add_i32 m0, s74, 0x2000
	s_nop 0
	global_load_lds_dwordx4 v[146:147], off
	s_waitcnt vmcnt(6)
	s_barrier
	s_setprio 1
	v_mfma_f32_16x16x32_bf16 v[52:55], v[208:211], v[168:171], v[52:55]
	v_mfma_f32_16x16x32_bf16 v[48:51], v[216:219], v[168:171], v[48:51]
	v_mfma_f32_16x16x32_bf16 v[36:39], v[208:211], v[176:179], v[36:39]
	v_mfma_f32_16x16x32_bf16 v[32:35], v[216:219], v[176:179], v[32:35]
	v_mfma_f32_16x16x32_bf16 v[20:23], v[208:211], v[192:195], v[20:23]
	v_mfma_f32_16x16x32_bf16 v[16:19], v[216:219], v[192:195], v[16:19]
	v_mfma_f32_16x16x32_bf16 v[4:7], v[208:211], v[200:203], v[4:7]
	v_mfma_f32_16x16x32_bf16 v[0:3], v[216:219], v[200:203], v[0:3]
	v_mfma_f32_16x16x32_bf16 v[52:55], v[212:215], v[172:175], v[52:55]
	v_mfma_f32_16x16x32_bf16 v[48:51], v[220:223], v[172:175], v[48:51]
	v_mfma_f32_16x16x32_bf16 v[36:39], v[212:215], v[180:183], v[36:39]
	v_mfma_f32_16x16x32_bf16 v[32:35], v[220:223], v[180:183], v[32:35]
	v_mfma_f32_16x16x32_bf16 v[20:23], v[212:215], v[196:199], v[20:23]
	v_mfma_f32_16x16x32_bf16 v[16:19], v[220:223], v[196:199], v[16:19]
	v_mfma_f32_16x16x32_bf16 v[4:7], v[212:215], v[204:207], v[4:7]
	v_mfma_f32_16x16x32_bf16 v[0:3], v[220:223], v[204:207], v[0:3]
	s_setprio 0
	s_add_i32 s95, s95, 2
	s_add_u32 s6, s6, 0x100
	s_addc_u32 s7, s7, 0
	s_add_u32 s92, s92, 0x100
	s_addc_u32 s93, s93, 0
	s_cmp_gt_u32 s95, 13
	s_barrier
	s_cbranch_scc0 .LBB0_242
	s_and_b32 s6, s0, -4
	s_cmp_eq_u32 s6, 8
	s_cselect_b64 s[6:7], -1, 0
	s_cmp_gt_i32 s0, 15
	s_cselect_b64 s[66:67], -1, 0
	s_or_b64 s[66:67], s[66:67], s[6:7]
	v_mov_b32_e32 v136, v254
	v_cndmask_b32_e64 v146, 0, 1, s[66:67]
	v_cmp_ne_u32_e64 s[6:7], 1, v146
	s_andn2_b64 vcc, exec, s[66:67]
	v_readfirstlane_b32 s13, v136
	s_cbranch_vccnz .LBB0_245
	s_mov_b32 s100, 0xbfb8aa3b
	v_pk_mul_f32 v[146:147], v[124:125], s[100:101] op_sel_hi:[1,0]
	v_pk_mul_f32 v[152:153], v[126:127], s[100:101] op_sel_hi:[1,0]
	v_pk_mul_f32 v[154:155], v[120:121], s[100:101] op_sel_hi:[1,0]
	v_pk_mul_f32 v[156:157], v[122:123], s[100:101] op_sel_hi:[1,0]
	v_exp_f32_e32 v146, v146
	v_exp_f32_e32 v147, v147
	v_exp_f32_e32 v152, v152
	v_exp_f32_e32 v153, v153
	v_exp_f32_e32 v154, v154
	v_exp_f32_e32 v155, v155
	v_exp_f32_e32 v156, v156
	v_exp_f32_e32 v157, v157
	v_pk_add_f32 v[146:147], v[146:147], 1.0 op_sel_hi:[1,0]
	v_pk_add_f32 v[152:153], v[152:153], 1.0 op_sel_hi:[1,0]
	v_pk_add_f32 v[154:155], v[154:155], 1.0 op_sel_hi:[1,0]
	v_pk_add_f32 v[156:157], v[156:157], 1.0 op_sel_hi:[1,0]
	v_rcp_f32_e32 v146, v146
	v_rcp_f32_e32 v147, v147
	v_rcp_f32_e32 v152, v152
	v_rcp_f32_e32 v153, v153
	v_rcp_f32_e32 v154, v154
	v_rcp_f32_e32 v156, v156
	v_rcp_f32_e32 v157, v157
	v_rcp_f32_e32 v155, v155
	v_pk_mul_f32 v[126:127], v[126:127], v[152:153]
	v_pk_mul_f32 v[124:125], v[124:125], v[146:147]
	v_pk_mul_f32 v[122:123], v[122:123], v[156:157]
	v_pk_mul_f32 v[120:121], v[120:121], v[154:155]
.LBB0_245:
	s_lshl_b32 s25, s60, 8
	s_ashr_i32 s60, s13, 2
	s_andn2_b32 s60, s60, 63
	s_add_i32 s60, s60, s25
	v_and_or_b32 v152, v136, 15, s60
	v_mov_b64_e32 v[146:147], s[22:23]
	v_mad_i64_i32 v[146:147], s[66:67], v152, s88, v[146:147]
	s_lshl_b32 s66, s0, 8
	s_ashr_i32 s67, s66, 31
	v_lshl_add_u64 v[146:147], s[66:67], 1, v[146:147]
	s_and_b32 s0, s13, 0xc0
	v_lshl_add_u64 v[146:147], v[146:147], 0, s[0:1]
	v_and_b32_e32 v136, 48, v136
	v_lshl_add_u64 v[146:147], v[146:147], 0, v[136:137]
	v_cvt_pk_bf16_f32 v124, v124, v125
	v_cvt_pk_bf16_f32 v125, v126, v127
	v_cvt_pk_bf16_f32 v126, v120, v121
	v_cvt_pk_bf16_f32 v127, v122, v123
	s_and_b64 vcc, exec, s[6:7]
	global_store_dwordx4 v[146:147], v[124:127], off
	s_cbranch_vccnz .LBB0_247
	s_mov_b32 s100, 0xbfb8aa3b
	v_pk_mul_f32 v[120:121], v[116:117], s[100:101] op_sel_hi:[1,0]
	v_pk_mul_f32 v[122:123], v[118:119], s[100:101] op_sel_hi:[1,0]
	v_pk_mul_f32 v[124:125], v[112:113], s[100:101] op_sel_hi:[1,0]
	v_pk_mul_f32 v[126:127], v[114:115], s[100:101] op_sel_hi:[1,0]
	v_exp_f32_e32 v120, v120
	v_exp_f32_e32 v121, v121
	v_exp_f32_e32 v122, v122
	v_exp_f32_e32 v123, v123
	v_exp_f32_e32 v124, v124
	v_exp_f32_e32 v125, v125
	v_exp_f32_e32 v126, v126
	v_exp_f32_e32 v127, v127
	v_pk_add_f32 v[120:121], v[120:121], 1.0 op_sel_hi:[1,0]
	v_pk_add_f32 v[122:123], v[122:123], 1.0 op_sel_hi:[1,0]
	v_pk_add_f32 v[124:125], v[124:125], 1.0 op_sel_hi:[1,0]
	v_pk_add_f32 v[126:127], v[126:127], 1.0 op_sel_hi:[1,0]
	v_rcp_f32_e32 v120, v120
	v_rcp_f32_e32 v121, v121
	v_rcp_f32_e32 v122, v122
	v_rcp_f32_e32 v123, v123
	v_rcp_f32_e32 v124, v124
	v_rcp_f32_e32 v126, v126
	v_rcp_f32_e32 v127, v127
	v_rcp_f32_e32 v125, v125
	v_pk_mul_f32 v[118:119], v[118:119], v[122:123]
	v_pk_mul_f32 v[116:117], v[116:117], v[120:121]
	v_pk_mul_f32 v[114:115], v[114:115], v[126:127]
	v_pk_mul_f32 v[112:113], v[112:113], v[124:125]
.LBB0_247:
	v_cvt_pk_bf16_f32 v116, v116, v117
	v_cvt_pk_bf16_f32 v117, v118, v119
	v_cvt_pk_bf16_f32 v118, v112, v113
	v_cvt_pk_bf16_f32 v119, v114, v115
	s_and_b64 vcc, exec, s[6:7]
	global_store_dwordx4 v[146:147], v[116:119], off offset:256
	s_cbranch_vccnz .LBB0_249
	s_mov_b32 s100, 0xbfb8aa3b
	v_pk_mul_f32 v[112:113], v[108:109], s[100:101] op_sel_hi:[1,0]
	v_pk_mul_f32 v[114:115], v[110:111], s[100:101] op_sel_hi:[1,0]
	v_pk_mul_f32 v[116:117], v[104:105], s[100:101] op_sel_hi:[1,0]
	v_pk_mul_f32 v[118:119], v[106:107], s[100:101] op_sel_hi:[1,0]
	v_exp_f32_e32 v112, v112
	v_exp_f32_e32 v113, v113
	v_exp_f32_e32 v114, v114
	v_exp_f32_e32 v115, v115
	v_exp_f32_e32 v116, v116
	v_exp_f32_e32 v117, v117
	v_exp_f32_e32 v118, v118
	v_exp_f32_e32 v119, v119
	v_pk_add_f32 v[112:113], v[112:113], 1.0 op_sel_hi:[1,0]
	v_pk_add_f32 v[114:115], v[114:115], 1.0 op_sel_hi:[1,0]
	v_pk_add_f32 v[116:117], v[116:117], 1.0 op_sel_hi:[1,0]
	v_pk_add_f32 v[118:119], v[118:119], 1.0 op_sel_hi:[1,0]
	v_rcp_f32_e32 v112, v112
	v_rcp_f32_e32 v113, v113
	v_rcp_f32_e32 v114, v114
	v_rcp_f32_e32 v115, v115
	v_rcp_f32_e32 v116, v116
	v_rcp_f32_e32 v118, v118
	v_rcp_f32_e32 v119, v119
	v_rcp_f32_e32 v117, v117
	v_pk_mul_f32 v[110:111], v[110:111], v[114:115]
	v_pk_mul_f32 v[108:109], v[108:109], v[112:113]
	v_pk_mul_f32 v[106:107], v[106:107], v[118:119]
	v_pk_mul_f32 v[104:105], v[104:105], v[116:117]
.LBB0_249:
	v_cvt_pk_bf16_f32 v108, v108, v109
	v_cvt_pk_bf16_f32 v109, v110, v111
	v_cvt_pk_bf16_f32 v110, v104, v105
	v_add_co_u32_e32 v104, vcc, 0x28000, v146
	v_cvt_pk_bf16_f32 v111, v106, v107
	s_nop 0
	v_addc_co_u32_e32 v105, vcc, 0, v147, vcc
	s_and_b64 vcc, exec, s[6:7]
	global_store_dwordx4 v[104:105], v[108:111], off
	s_cbranch_vccnz .LBB0_251
	s_mov_b32 s100, 0xbfb8aa3b
	v_pk_mul_f32 v[104:105], v[100:101], s[100:101] op_sel_hi:[1,0]
	v_pk_mul_f32 v[106:107], v[102:103], s[100:101] op_sel_hi:[1,0]
	v_pk_mul_f32 v[108:109], v[96:97], s[100:101] op_sel_hi:[1,0]
	v_pk_mul_f32 v[110:111], v[98:99], s[100:101] op_sel_hi:[1,0]
	v_exp_f32_e32 v104, v104
	v_exp_f32_e32 v105, v105
	v_exp_f32_e32 v106, v106
	v_exp_f32_e32 v107, v107
	v_exp_f32_e32 v108, v108
	v_exp_f32_e32 v109, v109
	v_exp_f32_e32 v110, v110
	v_exp_f32_e32 v111, v111
	v_pk_add_f32 v[104:105], v[104:105], 1.0 op_sel_hi:[1,0]
	v_pk_add_f32 v[106:107], v[106:107], 1.0 op_sel_hi:[1,0]
	v_pk_add_f32 v[108:109], v[108:109], 1.0 op_sel_hi:[1,0]
	v_pk_add_f32 v[110:111], v[110:111], 1.0 op_sel_hi:[1,0]
	v_rcp_f32_e32 v104, v104
	v_rcp_f32_e32 v105, v105
	v_rcp_f32_e32 v106, v106
	v_rcp_f32_e32 v107, v107
	v_rcp_f32_e32 v108, v108
	v_rcp_f32_e32 v110, v110
	v_rcp_f32_e32 v111, v111
	v_rcp_f32_e32 v109, v109
	v_pk_mul_f32 v[102:103], v[102:103], v[106:107]
	v_pk_mul_f32 v[100:101], v[100:101], v[104:105]
	v_pk_mul_f32 v[98:99], v[98:99], v[110:111]
	v_pk_mul_f32 v[96:97], v[96:97], v[108:109]
.LBB0_251:
	v_cvt_pk_bf16_f32 v100, v100, v101
	v_cvt_pk_bf16_f32 v101, v102, v103
	v_cvt_pk_bf16_f32 v102, v96, v97
	v_add_co_u32_e32 v96, vcc, 0x28000, v146
	v_cvt_pk_bf16_f32 v103, v98, v99
	s_nop 0
	v_addc_co_u32_e32 v97, vcc, 0, v147, vcc
	s_and_b64 vcc, exec, s[6:7]
	global_store_dwordx4 v[96:97], v[100:103], off offset:256
	s_cbranch_vccnz .LBB0_253
	s_mov_b32 s100, 0xbfb8aa3b
	v_pk_mul_f32 v[96:97], v[92:93], s[100:101] op_sel_hi:[1,0]
	v_pk_mul_f32 v[98:99], v[94:95], s[100:101] op_sel_hi:[1,0]
	v_pk_mul_f32 v[100:101], v[88:89], s[100:101] op_sel_hi:[1,0]
	v_pk_mul_f32 v[102:103], v[90:91], s[100:101] op_sel_hi:[1,0]
	v_exp_f32_e32 v96, v96
	v_exp_f32_e32 v97, v97
	v_exp_f32_e32 v98, v98
	v_exp_f32_e32 v99, v99
	v_exp_f32_e32 v100, v100
	v_exp_f32_e32 v101, v101
	v_exp_f32_e32 v102, v102
	v_exp_f32_e32 v103, v103
	v_pk_add_f32 v[96:97], v[96:97], 1.0 op_sel_hi:[1,0]
	v_pk_add_f32 v[98:99], v[98:99], 1.0 op_sel_hi:[1,0]
	v_pk_add_f32 v[100:101], v[100:101], 1.0 op_sel_hi:[1,0]
	v_pk_add_f32 v[102:103], v[102:103], 1.0 op_sel_hi:[1,0]
	v_rcp_f32_e32 v96, v96
	v_rcp_f32_e32 v97, v97
	v_rcp_f32_e32 v98, v98
	v_rcp_f32_e32 v99, v99
	v_rcp_f32_e32 v100, v100
	v_rcp_f32_e32 v102, v102
	v_rcp_f32_e32 v103, v103
	v_rcp_f32_e32 v101, v101
	v_pk_mul_f32 v[94:95], v[94:95], v[98:99]
	v_pk_mul_f32 v[92:93], v[92:93], v[96:97]
	v_pk_mul_f32 v[90:91], v[90:91], v[102:103]
	v_pk_mul_f32 v[88:89], v[88:89], v[100:101]
.LBB0_253:
	v_cvt_pk_bf16_f32 v92, v92, v93
	v_cvt_pk_bf16_f32 v93, v94, v95
	v_cvt_pk_bf16_f32 v94, v88, v89
	v_add_co_u32_e32 v88, vcc, 0x50000, v146
	v_cvt_pk_bf16_f32 v95, v90, v91
	s_nop 0
	v_addc_co_u32_e32 v89, vcc, 0, v147, vcc
	s_and_b64 vcc, exec, s[6:7]
	global_store_dwordx4 v[88:89], v[92:95], off
	s_cbranch_vccnz .LBB0_255
	s_mov_b32 s100, 0xbfb8aa3b
	v_pk_mul_f32 v[88:89], v[84:85], s[100:101] op_sel_hi:[1,0]
	v_pk_mul_f32 v[90:91], v[86:87], s[100:101] op_sel_hi:[1,0]
	v_pk_mul_f32 v[92:93], v[80:81], s[100:101] op_sel_hi:[1,0]
	v_pk_mul_f32 v[94:95], v[82:83], s[100:101] op_sel_hi:[1,0]
	v_exp_f32_e32 v88, v88
	v_exp_f32_e32 v89, v89
	v_exp_f32_e32 v90, v90
	v_exp_f32_e32 v91, v91
	v_exp_f32_e32 v92, v92
	v_exp_f32_e32 v93, v93
	v_exp_f32_e32 v94, v94
	v_exp_f32_e32 v95, v95
	v_pk_add_f32 v[88:89], v[88:89], 1.0 op_sel_hi:[1,0]
	v_pk_add_f32 v[90:91], v[90:91], 1.0 op_sel_hi:[1,0]
	v_pk_add_f32 v[92:93], v[92:93], 1.0 op_sel_hi:[1,0]
	v_pk_add_f32 v[94:95], v[94:95], 1.0 op_sel_hi:[1,0]
	v_rcp_f32_e32 v88, v88
	v_rcp_f32_e32 v89, v89
	v_rcp_f32_e32 v90, v90
	v_rcp_f32_e32 v91, v91
	v_rcp_f32_e32 v92, v92
	v_rcp_f32_e32 v94, v94
	v_rcp_f32_e32 v95, v95
	v_rcp_f32_e32 v93, v93
	v_pk_mul_f32 v[86:87], v[86:87], v[90:91]
	v_pk_mul_f32 v[84:85], v[84:85], v[88:89]
	v_pk_mul_f32 v[82:83], v[82:83], v[94:95]
	v_pk_mul_f32 v[80:81], v[80:81], v[92:93]
.LBB0_255:
	v_cvt_pk_bf16_f32 v84, v84, v85
	v_cvt_pk_bf16_f32 v85, v86, v87
	v_cvt_pk_bf16_f32 v86, v80, v81
	v_add_co_u32_e32 v80, vcc, 0x50000, v146
	v_cvt_pk_bf16_f32 v87, v82, v83
	s_nop 0
	v_addc_co_u32_e32 v81, vcc, 0, v147, vcc
	s_and_b64 vcc, exec, s[6:7]
	global_store_dwordx4 v[80:81], v[84:87], off offset:256
	s_cbranch_vccnz .LBB0_257
	s_mov_b32 s100, 0xbfb8aa3b
	v_pk_mul_f32 v[80:81], v[76:77], s[100:101] op_sel_hi:[1,0]
	v_pk_mul_f32 v[82:83], v[78:79], s[100:101] op_sel_hi:[1,0]
	v_pk_mul_f32 v[84:85], v[72:73], s[100:101] op_sel_hi:[1,0]
	v_pk_mul_f32 v[86:87], v[74:75], s[100:101] op_sel_hi:[1,0]
	v_exp_f32_e32 v80, v80
	v_exp_f32_e32 v81, v81
	v_exp_f32_e32 v82, v82
	v_exp_f32_e32 v83, v83
	v_exp_f32_e32 v84, v84
	v_exp_f32_e32 v85, v85
	v_exp_f32_e32 v86, v86
	v_exp_f32_e32 v87, v87
	v_pk_add_f32 v[80:81], v[80:81], 1.0 op_sel_hi:[1,0]
	v_pk_add_f32 v[82:83], v[82:83], 1.0 op_sel_hi:[1,0]
	v_pk_add_f32 v[84:85], v[84:85], 1.0 op_sel_hi:[1,0]
	v_pk_add_f32 v[86:87], v[86:87], 1.0 op_sel_hi:[1,0]
	v_rcp_f32_e32 v80, v80
	v_rcp_f32_e32 v81, v81
	v_rcp_f32_e32 v82, v82
	v_rcp_f32_e32 v83, v83
	v_rcp_f32_e32 v84, v84
	v_rcp_f32_e32 v86, v86
	v_rcp_f32_e32 v87, v87
	v_rcp_f32_e32 v85, v85
	v_pk_mul_f32 v[78:79], v[78:79], v[82:83]
	v_pk_mul_f32 v[76:77], v[76:77], v[80:81]
	v_pk_mul_f32 v[74:75], v[74:75], v[86:87]
	v_pk_mul_f32 v[72:73], v[72:73], v[84:85]
.LBB0_257:
	v_cvt_pk_bf16_f32 v76, v76, v77
	v_cvt_pk_bf16_f32 v77, v78, v79
	v_cvt_pk_bf16_f32 v78, v72, v73
	v_add_co_u32_e32 v72, vcc, 0x78000, v146
	v_cvt_pk_bf16_f32 v79, v74, v75
	s_nop 0
	v_addc_co_u32_e32 v73, vcc, 0, v147, vcc
	s_and_b64 vcc, exec, s[6:7]
	global_store_dwordx4 v[72:73], v[76:79], off
	s_cbranch_vccnz .LBB0_259
	s_mov_b32 s100, 0xbfb8aa3b
	v_pk_mul_f32 v[72:73], v[68:69], s[100:101] op_sel_hi:[1,0]
	v_pk_mul_f32 v[74:75], v[70:71], s[100:101] op_sel_hi:[1,0]
	v_pk_mul_f32 v[76:77], v[64:65], s[100:101] op_sel_hi:[1,0]
	v_pk_mul_f32 v[78:79], v[66:67], s[100:101] op_sel_hi:[1,0]
	v_exp_f32_e32 v72, v72
	v_exp_f32_e32 v73, v73
	v_exp_f32_e32 v74, v74
	v_exp_f32_e32 v75, v75
	v_exp_f32_e32 v76, v76
	v_exp_f32_e32 v77, v77
	v_exp_f32_e32 v78, v78
	v_exp_f32_e32 v79, v79
	v_pk_add_f32 v[72:73], v[72:73], 1.0 op_sel_hi:[1,0]
	v_pk_add_f32 v[74:75], v[74:75], 1.0 op_sel_hi:[1,0]
	v_pk_add_f32 v[76:77], v[76:77], 1.0 op_sel_hi:[1,0]
	v_pk_add_f32 v[78:79], v[78:79], 1.0 op_sel_hi:[1,0]
	v_rcp_f32_e32 v72, v72
	v_rcp_f32_e32 v73, v73
	v_rcp_f32_e32 v74, v74
	v_rcp_f32_e32 v75, v75
	v_rcp_f32_e32 v76, v76
	v_rcp_f32_e32 v78, v78
	v_rcp_f32_e32 v79, v79
	v_rcp_f32_e32 v77, v77
	v_pk_mul_f32 v[70:71], v[70:71], v[74:75]
	v_pk_mul_f32 v[68:69], v[68:69], v[72:73]
	v_pk_mul_f32 v[66:67], v[66:67], v[78:79]
	v_pk_mul_f32 v[64:65], v[64:65], v[76:77]
.LBB0_259:
	v_cvt_pk_bf16_f32 v68, v68, v69
	v_cvt_pk_bf16_f32 v69, v70, v71
	v_cvt_pk_bf16_f32 v70, v64, v65
	v_add_co_u32_e32 v64, vcc, 0x78000, v146
	v_cvt_pk_bf16_f32 v71, v66, v67
	s_nop 0
	v_addc_co_u32_e32 v65, vcc, 0, v147, vcc
	s_and_b64 vcc, exec, s[6:7]
	global_store_dwordx4 v[64:65], v[68:71], off offset:256
	s_cbranch_vccnz .LBB0_261
	s_mov_b32 s100, 0xbfb8aa3b
	v_pk_mul_f32 v[64:65], v[60:61], s[100:101] op_sel_hi:[1,0]
	v_pk_mul_f32 v[66:67], v[62:63], s[100:101] op_sel_hi:[1,0]
	v_pk_mul_f32 v[68:69], v[56:57], s[100:101] op_sel_hi:[1,0]
	v_pk_mul_f32 v[70:71], v[58:59], s[100:101] op_sel_hi:[1,0]
	v_exp_f32_e32 v64, v64
	v_exp_f32_e32 v65, v65
	v_exp_f32_e32 v66, v66
	v_exp_f32_e32 v67, v67
	v_exp_f32_e32 v68, v68
	v_exp_f32_e32 v69, v69
	v_exp_f32_e32 v70, v70
	v_exp_f32_e32 v71, v71
	v_pk_add_f32 v[64:65], v[64:65], 1.0 op_sel_hi:[1,0]
	v_pk_add_f32 v[66:67], v[66:67], 1.0 op_sel_hi:[1,0]
	v_pk_add_f32 v[68:69], v[68:69], 1.0 op_sel_hi:[1,0]
	v_pk_add_f32 v[70:71], v[70:71], 1.0 op_sel_hi:[1,0]
	v_rcp_f32_e32 v64, v64
	v_rcp_f32_e32 v65, v65
	v_rcp_f32_e32 v66, v66
	v_rcp_f32_e32 v67, v67
	v_rcp_f32_e32 v68, v68
	v_rcp_f32_e32 v70, v70
	v_rcp_f32_e32 v71, v71
	v_rcp_f32_e32 v69, v69
	v_pk_mul_f32 v[62:63], v[62:63], v[66:67]
	v_pk_mul_f32 v[60:61], v[60:61], v[64:65]
	v_pk_mul_f32 v[58:59], v[58:59], v[70:71]
	v_pk_mul_f32 v[56:57], v[56:57], v[68:69]
.LBB0_261:
	v_cvt_pk_bf16_f32 v60, v60, v61
	v_cvt_pk_bf16_f32 v61, v62, v63
	v_cvt_pk_bf16_f32 v62, v56, v57
	v_add_co_u32_e32 v56, vcc, 0x140000, v146
	v_cvt_pk_bf16_f32 v63, v58, v59
	s_nop 0
	v_addc_co_u32_e32 v57, vcc, 0, v147, vcc
	s_and_b64 vcc, exec, s[6:7]
	global_store_dwordx4 v[56:57], v[60:63], off
	s_cbranch_vccnz .LBB0_263
	s_mov_b32 s100, 0xbfb8aa3b
	v_pk_mul_f32 v[56:57], v[52:53], s[100:101] op_sel_hi:[1,0]
	v_pk_mul_f32 v[58:59], v[54:55], s[100:101] op_sel_hi:[1,0]
	v_pk_mul_f32 v[60:61], v[48:49], s[100:101] op_sel_hi:[1,0]
	v_pk_mul_f32 v[62:63], v[50:51], s[100:101] op_sel_hi:[1,0]
	v_exp_f32_e32 v56, v56
	v_exp_f32_e32 v57, v57
	v_exp_f32_e32 v58, v58
	v_exp_f32_e32 v59, v59
	v_exp_f32_e32 v60, v60
	v_exp_f32_e32 v61, v61
	v_exp_f32_e32 v62, v62
	v_exp_f32_e32 v63, v63
	v_pk_add_f32 v[56:57], v[56:57], 1.0 op_sel_hi:[1,0]
	v_pk_add_f32 v[58:59], v[58:59], 1.0 op_sel_hi:[1,0]
	v_pk_add_f32 v[60:61], v[60:61], 1.0 op_sel_hi:[1,0]
	v_pk_add_f32 v[62:63], v[62:63], 1.0 op_sel_hi:[1,0]
	v_rcp_f32_e32 v56, v56
	v_rcp_f32_e32 v57, v57
	v_rcp_f32_e32 v58, v58
	v_rcp_f32_e32 v59, v59
	v_rcp_f32_e32 v60, v60
	v_rcp_f32_e32 v62, v62
	v_rcp_f32_e32 v63, v63
	v_rcp_f32_e32 v61, v61
	v_pk_mul_f32 v[54:55], v[54:55], v[58:59]
	v_pk_mul_f32 v[52:53], v[52:53], v[56:57]
	v_pk_mul_f32 v[50:51], v[50:51], v[62:63]
	v_pk_mul_f32 v[48:49], v[48:49], v[60:61]
.LBB0_263:
	v_cvt_pk_bf16_f32 v52, v52, v53
	v_cvt_pk_bf16_f32 v53, v54, v55
	v_cvt_pk_bf16_f32 v54, v48, v49
	v_add_co_u32_e32 v48, vcc, 0x140000, v146
	v_cvt_pk_bf16_f32 v55, v50, v51
	s_nop 0
	v_addc_co_u32_e32 v49, vcc, 0, v147, vcc
	s_and_b64 vcc, exec, s[6:7]
	global_store_dwordx4 v[48:49], v[52:55], off offset:256
	s_cbranch_vccnz .LBB0_265
	s_mov_b32 s100, 0xbfb8aa3b
	v_pk_mul_f32 v[48:49], v[44:45], s[100:101] op_sel_hi:[1,0]
	v_pk_mul_f32 v[50:51], v[46:47], s[100:101] op_sel_hi:[1,0]
	v_pk_mul_f32 v[52:53], v[40:41], s[100:101] op_sel_hi:[1,0]
	v_pk_mul_f32 v[54:55], v[42:43], s[100:101] op_sel_hi:[1,0]
	v_exp_f32_e32 v48, v48
	v_exp_f32_e32 v49, v49
	v_exp_f32_e32 v50, v50
	v_exp_f32_e32 v51, v51
	v_exp_f32_e32 v52, v52
	v_exp_f32_e32 v53, v53
	v_exp_f32_e32 v54, v54
	v_exp_f32_e32 v55, v55
	v_pk_add_f32 v[48:49], v[48:49], 1.0 op_sel_hi:[1,0]
	v_pk_add_f32 v[50:51], v[50:51], 1.0 op_sel_hi:[1,0]
	v_pk_add_f32 v[52:53], v[52:53], 1.0 op_sel_hi:[1,0]
	v_pk_add_f32 v[54:55], v[54:55], 1.0 op_sel_hi:[1,0]
	v_rcp_f32_e32 v48, v48
	v_rcp_f32_e32 v49, v49
	v_rcp_f32_e32 v50, v50
	v_rcp_f32_e32 v51, v51
	v_rcp_f32_e32 v52, v52
	v_rcp_f32_e32 v54, v54
	v_rcp_f32_e32 v55, v55
	v_rcp_f32_e32 v53, v53
	v_pk_mul_f32 v[46:47], v[46:47], v[50:51]
	v_pk_mul_f32 v[44:45], v[44:45], v[48:49]
	v_pk_mul_f32 v[42:43], v[42:43], v[54:55]
	v_pk_mul_f32 v[40:41], v[40:41], v[52:53]
.LBB0_265:
	v_cvt_pk_bf16_f32 v44, v44, v45
	v_cvt_pk_bf16_f32 v45, v46, v47
	v_cvt_pk_bf16_f32 v46, v40, v41
	v_add_co_u32_e32 v40, vcc, 0x168000, v146
	v_cvt_pk_bf16_f32 v47, v42, v43
	s_nop 0
	v_addc_co_u32_e32 v41, vcc, 0, v147, vcc
	s_and_b64 vcc, exec, s[6:7]
	global_store_dwordx4 v[40:41], v[44:47], off
	s_cbranch_vccnz .LBB0_267
	s_mov_b32 s100, 0xbfb8aa3b
	v_pk_mul_f32 v[40:41], v[36:37], s[100:101] op_sel_hi:[1,0]
	v_pk_mul_f32 v[42:43], v[38:39], s[100:101] op_sel_hi:[1,0]
	v_pk_mul_f32 v[44:45], v[32:33], s[100:101] op_sel_hi:[1,0]
	v_pk_mul_f32 v[46:47], v[34:35], s[100:101] op_sel_hi:[1,0]
	v_exp_f32_e32 v40, v40
	v_exp_f32_e32 v41, v41
	v_exp_f32_e32 v42, v42
	v_exp_f32_e32 v43, v43
	v_exp_f32_e32 v44, v44
	v_exp_f32_e32 v45, v45
	v_exp_f32_e32 v46, v46
	v_exp_f32_e32 v47, v47
	v_pk_add_f32 v[40:41], v[40:41], 1.0 op_sel_hi:[1,0]
	v_pk_add_f32 v[42:43], v[42:43], 1.0 op_sel_hi:[1,0]
	v_pk_add_f32 v[44:45], v[44:45], 1.0 op_sel_hi:[1,0]
	v_pk_add_f32 v[46:47], v[46:47], 1.0 op_sel_hi:[1,0]
	v_rcp_f32_e32 v40, v40
	v_rcp_f32_e32 v41, v41
	v_rcp_f32_e32 v42, v42
	v_rcp_f32_e32 v43, v43
	v_rcp_f32_e32 v44, v44
	v_rcp_f32_e32 v46, v46
	v_rcp_f32_e32 v47, v47
	v_rcp_f32_e32 v45, v45
	v_pk_mul_f32 v[38:39], v[38:39], v[42:43]
	v_pk_mul_f32 v[36:37], v[36:37], v[40:41]
	v_pk_mul_f32 v[34:35], v[34:35], v[46:47]
	v_pk_mul_f32 v[32:33], v[32:33], v[44:45]
.LBB0_267:
	v_cvt_pk_bf16_f32 v36, v36, v37
	v_cvt_pk_bf16_f32 v37, v38, v39
	v_cvt_pk_bf16_f32 v38, v32, v33
	v_add_co_u32_e32 v32, vcc, 0x168000, v146
	v_cvt_pk_bf16_f32 v39, v34, v35
	s_nop 0
	v_addc_co_u32_e32 v33, vcc, 0, v147, vcc
	s_and_b64 vcc, exec, s[6:7]
	global_store_dwordx4 v[32:33], v[36:39], off offset:256
	s_cbranch_vccnz .LBB0_269
	s_mov_b32 s100, 0xbfb8aa3b
	v_pk_mul_f32 v[32:33], v[28:29], s[100:101] op_sel_hi:[1,0]
	v_pk_mul_f32 v[34:35], v[30:31], s[100:101] op_sel_hi:[1,0]
	v_pk_mul_f32 v[36:37], v[24:25], s[100:101] op_sel_hi:[1,0]
	v_pk_mul_f32 v[38:39], v[26:27], s[100:101] op_sel_hi:[1,0]
	v_exp_f32_e32 v32, v32
	v_exp_f32_e32 v33, v33
	v_exp_f32_e32 v34, v34
	v_exp_f32_e32 v35, v35
	v_exp_f32_e32 v36, v36
	v_exp_f32_e32 v37, v37
	v_exp_f32_e32 v38, v38
	v_exp_f32_e32 v39, v39
	v_pk_add_f32 v[32:33], v[32:33], 1.0 op_sel_hi:[1,0]
	v_pk_add_f32 v[34:35], v[34:35], 1.0 op_sel_hi:[1,0]
	v_pk_add_f32 v[36:37], v[36:37], 1.0 op_sel_hi:[1,0]
	v_pk_add_f32 v[38:39], v[38:39], 1.0 op_sel_hi:[1,0]
	v_rcp_f32_e32 v32, v32
	v_rcp_f32_e32 v33, v33
	v_rcp_f32_e32 v34, v34
	v_rcp_f32_e32 v35, v35
	v_rcp_f32_e32 v36, v36
	v_rcp_f32_e32 v38, v38
	v_rcp_f32_e32 v39, v39
	v_rcp_f32_e32 v37, v37
	v_pk_mul_f32 v[30:31], v[30:31], v[34:35]
	v_pk_mul_f32 v[28:29], v[28:29], v[32:33]
	v_pk_mul_f32 v[26:27], v[26:27], v[38:39]
	v_pk_mul_f32 v[24:25], v[24:25], v[36:37]
.LBB0_269:
	v_cvt_pk_bf16_f32 v28, v28, v29
	v_cvt_pk_bf16_f32 v29, v30, v31
	v_cvt_pk_bf16_f32 v30, v24, v25
	v_add_co_u32_e32 v24, vcc, 0x190000, v146
	v_cvt_pk_bf16_f32 v31, v26, v27
	s_nop 0
	v_addc_co_u32_e32 v25, vcc, 0, v147, vcc
	s_and_b64 vcc, exec, s[6:7]
	global_store_dwordx4 v[24:25], v[28:31], off
	s_cbranch_vccnz .LBB0_271
	s_mov_b32 s100, 0xbfb8aa3b
	v_pk_mul_f32 v[24:25], v[20:21], s[100:101] op_sel_hi:[1,0]
	v_pk_mul_f32 v[26:27], v[22:23], s[100:101] op_sel_hi:[1,0]
	v_pk_mul_f32 v[28:29], v[16:17], s[100:101] op_sel_hi:[1,0]
	v_pk_mul_f32 v[30:31], v[18:19], s[100:101] op_sel_hi:[1,0]
	v_exp_f32_e32 v24, v24
	v_exp_f32_e32 v25, v25
	v_exp_f32_e32 v26, v26
	v_exp_f32_e32 v27, v27
	v_exp_f32_e32 v28, v28
	v_exp_f32_e32 v29, v29
	v_exp_f32_e32 v30, v30
	v_exp_f32_e32 v31, v31
	v_pk_add_f32 v[24:25], v[24:25], 1.0 op_sel_hi:[1,0]
	v_pk_add_f32 v[26:27], v[26:27], 1.0 op_sel_hi:[1,0]
	v_pk_add_f32 v[28:29], v[28:29], 1.0 op_sel_hi:[1,0]
	v_pk_add_f32 v[30:31], v[30:31], 1.0 op_sel_hi:[1,0]
	v_rcp_f32_e32 v24, v24
	v_rcp_f32_e32 v25, v25
	v_rcp_f32_e32 v26, v26
	v_rcp_f32_e32 v27, v27
	v_rcp_f32_e32 v28, v28
	v_rcp_f32_e32 v30, v30
	v_rcp_f32_e32 v31, v31
	v_rcp_f32_e32 v29, v29
	v_pk_mul_f32 v[22:23], v[22:23], v[26:27]
	v_pk_mul_f32 v[20:21], v[20:21], v[24:25]
	v_pk_mul_f32 v[18:19], v[18:19], v[30:31]
	v_pk_mul_f32 v[16:17], v[16:17], v[28:29]
.LBB0_271:
	v_cvt_pk_bf16_f32 v20, v20, v21
	v_cvt_pk_bf16_f32 v21, v22, v23
	v_cvt_pk_bf16_f32 v22, v16, v17
	v_add_co_u32_e32 v16, vcc, 0x190000, v146
	v_cvt_pk_bf16_f32 v23, v18, v19
	s_nop 0
	v_addc_co_u32_e32 v17, vcc, 0, v147, vcc
	s_and_b64 vcc, exec, s[6:7]
	global_store_dwordx4 v[16:17], v[20:23], off offset:256
	s_cbranch_vccnz .LBB0_273
	s_mov_b32 s100, 0xbfb8aa3b
	v_pk_mul_f32 v[16:17], v[12:13], s[100:101] op_sel_hi:[1,0]
	v_pk_mul_f32 v[18:19], v[14:15], s[100:101] op_sel_hi:[1,0]
	v_pk_mul_f32 v[20:21], v[8:9], s[100:101] op_sel_hi:[1,0]
	v_pk_mul_f32 v[22:23], v[10:11], s[100:101] op_sel_hi:[1,0]
	v_exp_f32_e32 v16, v16
	v_exp_f32_e32 v17, v17
	v_exp_f32_e32 v18, v18
	v_exp_f32_e32 v19, v19
	v_exp_f32_e32 v20, v20
	v_exp_f32_e32 v21, v21
	v_exp_f32_e32 v22, v22
	v_exp_f32_e32 v23, v23
	v_pk_add_f32 v[16:17], v[16:17], 1.0 op_sel_hi:[1,0]
	v_pk_add_f32 v[18:19], v[18:19], 1.0 op_sel_hi:[1,0]
	v_pk_add_f32 v[20:21], v[20:21], 1.0 op_sel_hi:[1,0]
	v_pk_add_f32 v[22:23], v[22:23], 1.0 op_sel_hi:[1,0]
	v_rcp_f32_e32 v16, v16
	v_rcp_f32_e32 v17, v17
	v_rcp_f32_e32 v18, v18
	v_rcp_f32_e32 v19, v19
	v_rcp_f32_e32 v20, v20
	v_rcp_f32_e32 v22, v22
	v_rcp_f32_e32 v23, v23
	v_rcp_f32_e32 v21, v21
	v_pk_mul_f32 v[14:15], v[14:15], v[18:19]
	v_pk_mul_f32 v[12:13], v[12:13], v[16:17]
	v_pk_mul_f32 v[10:11], v[10:11], v[22:23]
	v_pk_mul_f32 v[8:9], v[8:9], v[20:21]
.LBB0_273:
	v_cvt_pk_bf16_f32 v12, v12, v13
	v_cvt_pk_bf16_f32 v13, v14, v15
	v_cvt_pk_bf16_f32 v14, v8, v9
	v_add_co_u32_e32 v8, vcc, 0x1b8000, v146
	v_cvt_pk_bf16_f32 v15, v10, v11
	s_nop 0
	v_addc_co_u32_e32 v9, vcc, 0, v147, vcc
	s_and_b64 vcc, exec, s[6:7]
	global_store_dwordx4 v[8:9], v[12:15], off
	s_cbranch_vccnz .LBB0_238
	s_mov_b32 s100, 0xbfb8aa3b
	v_pk_mul_f32 v[8:9], v[4:5], s[100:101] op_sel_hi:[1,0]
	v_pk_mul_f32 v[10:11], v[6:7], s[100:101] op_sel_hi:[1,0]
	v_pk_mul_f32 v[12:13], v[0:1], s[100:101] op_sel_hi:[1,0]
	v_pk_mul_f32 v[14:15], v[2:3], s[100:101] op_sel_hi:[1,0]
	v_exp_f32_e32 v8, v8
	v_exp_f32_e32 v9, v9
	v_exp_f32_e32 v10, v10
	v_exp_f32_e32 v11, v11
	v_exp_f32_e32 v12, v12
	v_exp_f32_e32 v13, v13
	v_exp_f32_e32 v14, v14
	v_exp_f32_e32 v15, v15
	v_pk_add_f32 v[8:9], v[8:9], 1.0 op_sel_hi:[1,0]
	v_pk_add_f32 v[10:11], v[10:11], 1.0 op_sel_hi:[1,0]
	v_pk_add_f32 v[12:13], v[12:13], 1.0 op_sel_hi:[1,0]
	v_pk_add_f32 v[14:15], v[14:15], 1.0 op_sel_hi:[1,0]
	v_rcp_f32_e32 v8, v8
	v_rcp_f32_e32 v9, v9
	v_rcp_f32_e32 v10, v10
	v_rcp_f32_e32 v11, v11
	v_rcp_f32_e32 v12, v12
	v_rcp_f32_e32 v14, v14
	v_rcp_f32_e32 v15, v15
	v_rcp_f32_e32 v13, v13
	v_pk_mul_f32 v[6:7], v[6:7], v[10:11]
	v_pk_mul_f32 v[4:5], v[4:5], v[8:9]
	v_pk_mul_f32 v[2:3], v[2:3], v[14:15]
	v_pk_mul_f32 v[0:1], v[0:1], v[12:13]
	s_branch .LBB0_238

.LBB0_623:
	v_cvt_pk_bf16_f32 v124, v124, v125
	v_cvt_pk_bf16_f32 v125, v126, v127
	v_cvt_pk_bf16_f32 v126, v120, v121
	v_cvt_pk_bf16_f32 v127, v122, v123
	s_and_b64 vcc, exec, s[6:7]
	global_store_dwordx4 v[146:147], v[124:127], off
	s_cbranch_vccnz .LBB0_625
	s_mov_b32 s100, 0xbfb8aa3b
	v_pk_mul_f32 v[120:121], v[116:117], s[100:101] op_sel_hi:[1,0]
	v_pk_mul_f32 v[122:123], v[118:119], s[100:101] op_sel_hi:[1,0]
	v_pk_mul_f32 v[124:125], v[112:113], s[100:101] op_sel_hi:[1,0]
	v_pk_mul_f32 v[126:127], v[114:115], s[100:101] op_sel_hi:[1,0]
	v_exp_f32_e32 v120, v120
	v_exp_f32_e32 v121, v121
	v_exp_f32_e32 v122, v122
	v_exp_f32_e32 v123, v123
	v_exp_f32_e32 v124, v124
	v_exp_f32_e32 v125, v125
	v_exp_f32_e32 v126, v126
	v_exp_f32_e32 v127, v127
	v_pk_add_f32 v[120:121], v[120:121], 1.0 op_sel_hi:[1,0]
	v_pk_add_f32 v[122:123], v[122:123], 1.0 op_sel_hi:[1,0]
	v_pk_add_f32 v[124:125], v[124:125], 1.0 op_sel_hi:[1,0]
	v_pk_add_f32 v[126:127], v[126:127], 1.0 op_sel_hi:[1,0]
	v_rcp_f32_e32 v120, v120
	v_rcp_f32_e32 v121, v121
	v_rcp_f32_e32 v122, v122
	v_rcp_f32_e32 v123, v123
	v_rcp_f32_e32 v124, v124
	v_rcp_f32_e32 v126, v126
	v_rcp_f32_e32 v127, v127
	v_rcp_f32_e32 v125, v125
	v_pk_mul_f32 v[118:119], v[118:119], v[122:123]
	v_pk_mul_f32 v[116:117], v[116:117], v[120:121]
	v_pk_mul_f32 v[114:115], v[114:115], v[126:127]
	v_pk_mul_f32 v[112:113], v[112:113], v[124:125]
.LBB0_625:
	s_lshl_b32 s58, s58, 1
	s_mov_b32 s59, s1
	v_cvt_pk_bf16_f32 v116, v116, v117
	v_cvt_pk_bf16_f32 v117, v118, v119
	v_cvt_pk_bf16_f32 v118, v112, v113
	v_cvt_pk_bf16_f32 v119, v114, v115
	v_lshl_add_u64 v[112:113], v[146:147], 0, s[58:59]
	s_and_b64 vcc, exec, s[6:7]
	global_store_dwordx4 v[112:113], v[116:119], off
	s_cbranch_vccnz .LBB0_627
	s_mov_b32 s100, 0xbfb8aa3b
	v_pk_mul_f32 v[112:113], v[108:109], s[100:101] op_sel_hi:[1,0]
	v_pk_mul_f32 v[114:115], v[110:111], s[100:101] op_sel_hi:[1,0]
	v_pk_mul_f32 v[116:117], v[104:105], s[100:101] op_sel_hi:[1,0]
	v_pk_mul_f32 v[118:119], v[106:107], s[100:101] op_sel_hi:[1,0]
	v_exp_f32_e32 v112, v112
	v_exp_f32_e32 v113, v113
	v_exp_f32_e32 v114, v114
	v_exp_f32_e32 v115, v115
	v_exp_f32_e32 v116, v116
	v_exp_f32_e32 v117, v117
	v_exp_f32_e32 v118, v118
	v_exp_f32_e32 v119, v119
	v_pk_add_f32 v[112:113], v[112:113], 1.0 op_sel_hi:[1,0]
	v_pk_add_f32 v[114:115], v[114:115], 1.0 op_sel_hi:[1,0]
	v_pk_add_f32 v[116:117], v[116:117], 1.0 op_sel_hi:[1,0]
	v_pk_add_f32 v[118:119], v[118:119], 1.0 op_sel_hi:[1,0]
	v_rcp_f32_e32 v112, v112
	v_rcp_f32_e32 v113, v113
	v_rcp_f32_e32 v114, v114
	v_rcp_f32_e32 v115, v115
	v_rcp_f32_e32 v116, v116
	v_rcp_f32_e32 v118, v118
	v_rcp_f32_e32 v119, v119
	v_rcp_f32_e32 v117, v117
	v_pk_mul_f32 v[110:111], v[110:111], v[114:115]
	v_pk_mul_f32 v[108:109], v[108:109], v[112:113]
	v_pk_mul_f32 v[106:107], v[106:107], v[118:119]
	v_pk_mul_f32 v[104:105], v[104:105], v[116:117]
.LBB0_627:
	s_lshl_b32 s0, s60, 5
	v_lshl_add_u64 v[112:113], v[146:147], 0, s[0:1]
	v_cvt_pk_bf16_f32 v108, v108, v109
	v_cvt_pk_bf16_f32 v109, v110, v111
	v_cvt_pk_bf16_f32 v110, v104, v105
	v_cvt_pk_bf16_f32 v111, v106, v107
	s_and_b64 vcc, exec, s[6:7]
	global_store_dwordx4 v[112:113], v[108:111], off
	s_cbranch_vccnz .LBB0_629
	s_mov_b32 s100, 0xbfb8aa3b
	v_pk_mul_f32 v[104:105], v[100:101], s[100:101] op_sel_hi:[1,0]
	v_pk_mul_f32 v[106:107], v[102:103], s[100:101] op_sel_hi:[1,0]
	v_pk_mul_f32 v[108:109], v[96:97], s[100:101] op_sel_hi:[1,0]
	v_pk_mul_f32 v[110:111], v[98:99], s[100:101] op_sel_hi:[1,0]
	v_exp_f32_e32 v104, v104
	v_exp_f32_e32 v105, v105
	v_exp_f32_e32 v106, v106
	v_exp_f32_e32 v107, v107
	v_exp_f32_e32 v108, v108
	v_exp_f32_e32 v109, v109
	v_exp_f32_e32 v110, v110
	v_exp_f32_e32 v111, v111
	v_pk_add_f32 v[104:105], v[104:105], 1.0 op_sel_hi:[1,0]
	v_pk_add_f32 v[106:107], v[106:107], 1.0 op_sel_hi:[1,0]
	v_pk_add_f32 v[108:109], v[108:109], 1.0 op_sel_hi:[1,0]
	v_pk_add_f32 v[110:111], v[110:111], 1.0 op_sel_hi:[1,0]
	v_rcp_f32_e32 v104, v104
	v_rcp_f32_e32 v105, v105
	v_rcp_f32_e32 v106, v106
	v_rcp_f32_e32 v107, v107
	v_rcp_f32_e32 v108, v108
	v_rcp_f32_e32 v110, v110
	v_rcp_f32_e32 v111, v111
	v_rcp_f32_e32 v109, v109
	v_pk_mul_f32 v[102:103], v[102:103], v[106:107]
	v_pk_mul_f32 v[100:101], v[100:101], v[104:105]
	v_pk_mul_f32 v[98:99], v[98:99], v[110:111]
	v_pk_mul_f32 v[96:97], v[96:97], v[108:109]
.LBB0_629:
	s_mov_b32 s59, s1
	v_cvt_pk_bf16_f32 v100, v100, v101
	v_cvt_pk_bf16_f32 v101, v102, v103
	v_cvt_pk_bf16_f32 v102, v96, v97
	v_cvt_pk_bf16_f32 v103, v98, v99
	v_lshl_add_u64 v[96:97], v[112:113], 0, s[58:59]
	s_and_b64 vcc, exec, s[6:7]
	global_store_dwordx4 v[96:97], v[100:103], off
	s_cbranch_vccnz .LBB0_631
	s_mov_b32 s100, 0xbfb8aa3b
	v_pk_mul_f32 v[96:97], v[92:93], s[100:101] op_sel_hi:[1,0]
	v_pk_mul_f32 v[98:99], v[94:95], s[100:101] op_sel_hi:[1,0]
	v_pk_mul_f32 v[100:101], v[88:89], s[100:101] op_sel_hi:[1,0]
	v_pk_mul_f32 v[102:103], v[90:91], s[100:101] op_sel_hi:[1,0]
	v_exp_f32_e32 v96, v96
	v_exp_f32_e32 v97, v97
	v_exp_f32_e32 v98, v98
	v_exp_f32_e32 v99, v99
	v_exp_f32_e32 v100, v100
	v_exp_f32_e32 v101, v101
	v_exp_f32_e32 v102, v102
	v_exp_f32_e32 v103, v103
	v_pk_add_f32 v[96:97], v[96:97], 1.0 op_sel_hi:[1,0]
	v_pk_add_f32 v[98:99], v[98:99], 1.0 op_sel_hi:[1,0]
	v_pk_add_f32 v[100:101], v[100:101], 1.0 op_sel_hi:[1,0]
	v_pk_add_f32 v[102:103], v[102:103], 1.0 op_sel_hi:[1,0]
	v_rcp_f32_e32 v96, v96
	v_rcp_f32_e32 v97, v97
	v_rcp_f32_e32 v98, v98
	v_rcp_f32_e32 v99, v99
	v_rcp_f32_e32 v100, v100
	v_rcp_f32_e32 v102, v102
	v_rcp_f32_e32 v103, v103
	v_rcp_f32_e32 v101, v101
	v_pk_mul_f32 v[94:95], v[94:95], v[98:99]
	v_pk_mul_f32 v[92:93], v[92:93], v[96:97]
	v_pk_mul_f32 v[90:91], v[90:91], v[102:103]
	v_pk_mul_f32 v[88:89], v[88:89], v[100:101]
.LBB0_631:
	v_lshl_add_u64 v[96:97], v[112:113], 0, s[0:1]
	v_cvt_pk_bf16_f32 v92, v92, v93
	v_cvt_pk_bf16_f32 v93, v94, v95
	v_cvt_pk_bf16_f32 v94, v88, v89
	v_cvt_pk_bf16_f32 v95, v90, v91
	s_and_b64 vcc, exec, s[6:7]
	global_store_dwordx4 v[96:97], v[92:95], off
	s_cbranch_vccnz .LBB0_633
	s_mov_b32 s100, 0xbfb8aa3b
	v_pk_mul_f32 v[88:89], v[84:85], s[100:101] op_sel_hi:[1,0]
	v_pk_mul_f32 v[90:91], v[86:87], s[100:101] op_sel_hi:[1,0]
	v_pk_mul_f32 v[92:93], v[80:81], s[100:101] op_sel_hi:[1,0]
	v_pk_mul_f32 v[94:95], v[82:83], s[100:101] op_sel_hi:[1,0]
	v_exp_f32_e32 v88, v88
	v_exp_f32_e32 v89, v89
	v_exp_f32_e32 v90, v90
	v_exp_f32_e32 v91, v91
	v_exp_f32_e32 v92, v92
	v_exp_f32_e32 v93, v93
	v_exp_f32_e32 v94, v94
	v_exp_f32_e32 v95, v95
	v_pk_add_f32 v[88:89], v[88:89], 1.0 op_sel_hi:[1,0]
	v_pk_add_f32 v[90:91], v[90:91], 1.0 op_sel_hi:[1,0]
	v_pk_add_f32 v[92:93], v[92:93], 1.0 op_sel_hi:[1,0]
	v_pk_add_f32 v[94:95], v[94:95], 1.0 op_sel_hi:[1,0]
	v_rcp_f32_e32 v88, v88
	v_rcp_f32_e32 v89, v89
	v_rcp_f32_e32 v90, v90
	v_rcp_f32_e32 v91, v91
	v_rcp_f32_e32 v92, v92
	v_rcp_f32_e32 v94, v94
	v_rcp_f32_e32 v95, v95
	v_rcp_f32_e32 v93, v93
	v_pk_mul_f32 v[86:87], v[86:87], v[90:91]
	v_pk_mul_f32 v[84:85], v[84:85], v[88:89]
	v_pk_mul_f32 v[82:83], v[82:83], v[94:95]
	v_pk_mul_f32 v[80:81], v[80:81], v[92:93]
.LBB0_633:
	s_mov_b32 s59, s1
	v_cvt_pk_bf16_f32 v84, v84, v85
	v_cvt_pk_bf16_f32 v85, v86, v87
	v_cvt_pk_bf16_f32 v86, v80, v81
	v_cvt_pk_bf16_f32 v87, v82, v83
	v_lshl_add_u64 v[80:81], v[96:97], 0, s[58:59]
	s_and_b64 vcc, exec, s[6:7]
	global_store_dwordx4 v[80:81], v[84:87], off
	s_cbranch_vccnz .LBB0_635
	s_mov_b32 s100, 0xbfb8aa3b
	v_pk_mul_f32 v[80:81], v[76:77], s[100:101] op_sel_hi:[1,0]
	v_pk_mul_f32 v[82:83], v[78:79], s[100:101] op_sel_hi:[1,0]
	v_pk_mul_f32 v[84:85], v[72:73], s[100:101] op_sel_hi:[1,0]
	v_pk_mul_f32 v[86:87], v[74:75], s[100:101] op_sel_hi:[1,0]
	v_exp_f32_e32 v80, v80
	v_exp_f32_e32 v81, v81
	v_exp_f32_e32 v82, v82
	v_exp_f32_e32 v83, v83
	v_exp_f32_e32 v84, v84
	v_exp_f32_e32 v85, v85
	v_exp_f32_e32 v86, v86
	v_exp_f32_e32 v87, v87
	v_pk_add_f32 v[80:81], v[80:81], 1.0 op_sel_hi:[1,0]
	v_pk_add_f32 v[82:83], v[82:83], 1.0 op_sel_hi:[1,0]
	v_pk_add_f32 v[84:85], v[84:85], 1.0 op_sel_hi:[1,0]
	v_pk_add_f32 v[86:87], v[86:87], 1.0 op_sel_hi:[1,0]
	v_rcp_f32_e32 v80, v80
	v_rcp_f32_e32 v81, v81
	v_rcp_f32_e32 v82, v82
	v_rcp_f32_e32 v83, v83
	v_rcp_f32_e32 v84, v84
	v_rcp_f32_e32 v86, v86
	v_rcp_f32_e32 v87, v87
	v_rcp_f32_e32 v85, v85
	v_pk_mul_f32 v[78:79], v[78:79], v[82:83]
	v_pk_mul_f32 v[76:77], v[76:77], v[80:81]
	v_pk_mul_f32 v[74:75], v[74:75], v[86:87]
	v_pk_mul_f32 v[72:73], v[72:73], v[84:85]
.LBB0_635:
	v_lshl_add_u64 v[80:81], v[96:97], 0, s[0:1]
	v_cvt_pk_bf16_f32 v76, v76, v77
	v_cvt_pk_bf16_f32 v77, v78, v79
	v_cvt_pk_bf16_f32 v78, v72, v73
	v_cvt_pk_bf16_f32 v79, v74, v75
	s_and_b64 vcc, exec, s[6:7]
	global_store_dwordx4 v[80:81], v[76:79], off
	s_cbranch_vccnz .LBB0_637
	s_mov_b32 s100, 0xbfb8aa3b
	v_pk_mul_f32 v[72:73], v[68:69], s[100:101] op_sel_hi:[1,0]
	v_pk_mul_f32 v[74:75], v[70:71], s[100:101] op_sel_hi:[1,0]
	v_pk_mul_f32 v[76:77], v[64:65], s[100:101] op_sel_hi:[1,0]
	v_pk_mul_f32 v[78:79], v[66:67], s[100:101] op_sel_hi:[1,0]
	v_exp_f32_e32 v72, v72
	v_exp_f32_e32 v73, v73
	v_exp_f32_e32 v74, v74
	v_exp_f32_e32 v75, v75
	v_exp_f32_e32 v76, v76
	v_exp_f32_e32 v77, v77
	v_exp_f32_e32 v78, v78
	v_exp_f32_e32 v79, v79
	v_pk_add_f32 v[72:73], v[72:73], 1.0 op_sel_hi:[1,0]
	v_pk_add_f32 v[74:75], v[74:75], 1.0 op_sel_hi:[1,0]
	v_pk_add_f32 v[76:77], v[76:77], 1.0 op_sel_hi:[1,0]
	v_pk_add_f32 v[78:79], v[78:79], 1.0 op_sel_hi:[1,0]
	v_rcp_f32_e32 v72, v72
	v_rcp_f32_e32 v73, v73
	v_rcp_f32_e32 v74, v74
	v_rcp_f32_e32 v75, v75
	v_rcp_f32_e32 v76, v76
	v_rcp_f32_e32 v78, v78
	v_rcp_f32_e32 v79, v79
	v_rcp_f32_e32 v77, v77
	v_pk_mul_f32 v[70:71], v[70:71], v[74:75]
	v_pk_mul_f32 v[68:69], v[68:69], v[72:73]
	v_pk_mul_f32 v[66:67], v[66:67], v[78:79]
	v_pk_mul_f32 v[64:65], v[64:65], v[76:77]
.LBB0_637:
	s_mov_b32 s59, s1
	v_cvt_pk_bf16_f32 v68, v68, v69
	v_cvt_pk_bf16_f32 v69, v70, v71
	v_cvt_pk_bf16_f32 v70, v64, v65
	v_cvt_pk_bf16_f32 v71, v66, v67
	v_lshl_add_u64 v[64:65], v[80:81], 0, s[58:59]
	s_and_b64 vcc, exec, s[6:7]
	global_store_dwordx4 v[64:65], v[68:71], off
	s_cbranch_vccnz .LBB0_639
	s_mov_b32 s100, 0xbfb8aa3b
	v_pk_mul_f32 v[64:65], v[60:61], s[100:101] op_sel_hi:[1,0]
	v_pk_mul_f32 v[66:67], v[62:63], s[100:101] op_sel_hi:[1,0]
	v_pk_mul_f32 v[68:69], v[56:57], s[100:101] op_sel_hi:[1,0]
	v_pk_mul_f32 v[70:71], v[58:59], s[100:101] op_sel_hi:[1,0]
	v_exp_f32_e32 v64, v64
	v_exp_f32_e32 v65, v65
	v_exp_f32_e32 v66, v66
	v_exp_f32_e32 v67, v67
	v_exp_f32_e32 v68, v68
	v_exp_f32_e32 v69, v69
	v_exp_f32_e32 v70, v70
	v_exp_f32_e32 v71, v71
	v_pk_add_f32 v[64:65], v[64:65], 1.0 op_sel_hi:[1,0]
	v_pk_add_f32 v[66:67], v[66:67], 1.0 op_sel_hi:[1,0]
	v_pk_add_f32 v[68:69], v[68:69], 1.0 op_sel_hi:[1,0]
	v_pk_add_f32 v[70:71], v[70:71], 1.0 op_sel_hi:[1,0]
	v_rcp_f32_e32 v64, v64
	v_rcp_f32_e32 v65, v65
	v_rcp_f32_e32 v66, v66
	v_rcp_f32_e32 v67, v67
	v_rcp_f32_e32 v68, v68
	v_rcp_f32_e32 v70, v70
	v_rcp_f32_e32 v71, v71
	v_rcp_f32_e32 v69, v69
	v_pk_mul_f32 v[62:63], v[62:63], v[66:67]
	v_pk_mul_f32 v[60:61], v[60:61], v[64:65]
	v_pk_mul_f32 v[58:59], v[58:59], v[70:71]
	v_pk_mul_f32 v[56:57], v[56:57], v[68:69]
.LBB0_639:
	s_mulk_i32 s60, 0xa0
	s_mov_b32 s61, s1
	v_lshl_add_u64 v[64:65], v[80:81], 0, s[60:61]
	v_cvt_pk_bf16_f32 v60, v60, v61
	v_cvt_pk_bf16_f32 v61, v62, v63
	v_cvt_pk_bf16_f32 v62, v56, v57
	v_cvt_pk_bf16_f32 v63, v58, v59
	s_and_b64 vcc, exec, s[6:7]
	global_store_dwordx4 v[64:65], v[60:63], off
	s_cbranch_vccnz .LBB0_641
	s_mov_b32 s100, 0xbfb8aa3b
	v_pk_mul_f32 v[56:57], v[52:53], s[100:101] op_sel_hi:[1,0]
	v_pk_mul_f32 v[58:59], v[54:55], s[100:101] op_sel_hi:[1,0]
	v_pk_mul_f32 v[60:61], v[48:49], s[100:101] op_sel_hi:[1,0]
	v_pk_mul_f32 v[62:63], v[50:51], s[100:101] op_sel_hi:[1,0]
	v_exp_f32_e32 v56, v56
	v_exp_f32_e32 v57, v57
	v_exp_f32_e32 v58, v58
	v_exp_f32_e32 v59, v59
	v_exp_f32_e32 v60, v60
	v_exp_f32_e32 v61, v61
	v_exp_f32_e32 v62, v62
	v_exp_f32_e32 v63, v63
	v_pk_add_f32 v[56:57], v[56:57], 1.0 op_sel_hi:[1,0]
	v_pk_add_f32 v[58:59], v[58:59], 1.0 op_sel_hi:[1,0]
	v_pk_add_f32 v[60:61], v[60:61], 1.0 op_sel_hi:[1,0]
	v_pk_add_f32 v[62:63], v[62:63], 1.0 op_sel_hi:[1,0]
	v_rcp_f32_e32 v56, v56
	v_rcp_f32_e32 v57, v57
	v_rcp_f32_e32 v58, v58
	v_rcp_f32_e32 v59, v59
	v_rcp_f32_e32 v60, v60
	v_rcp_f32_e32 v62, v62
	v_rcp_f32_e32 v63, v63
	v_rcp_f32_e32 v61, v61
	v_pk_mul_f32 v[54:55], v[54:55], v[58:59]
	v_pk_mul_f32 v[52:53], v[52:53], v[56:57]
	v_pk_mul_f32 v[50:51], v[50:51], v[62:63]
	v_pk_mul_f32 v[48:49], v[48:49], v[60:61]
.LBB0_641:
	s_mov_b32 s59, s1
	v_cvt_pk_bf16_f32 v52, v52, v53
	v_cvt_pk_bf16_f32 v53, v54, v55
	v_cvt_pk_bf16_f32 v54, v48, v49
	v_cvt_pk_bf16_f32 v55, v50, v51
	v_lshl_add_u64 v[48:49], v[64:65], 0, s[58:59]
	s_and_b64 vcc, exec, s[6:7]
	global_store_dwordx4 v[48:49], v[52:55], off
	s_cbranch_vccnz .LBB0_643
	s_mov_b32 s100, 0xbfb8aa3b
	v_pk_mul_f32 v[48:49], v[44:45], s[100:101] op_sel_hi:[1,0]
	v_pk_mul_f32 v[50:51], v[46:47], s[100:101] op_sel_hi:[1,0]
	v_pk_mul_f32 v[52:53], v[40:41], s[100:101] op_sel_hi:[1,0]
	v_pk_mul_f32 v[54:55], v[42:43], s[100:101] op_sel_hi:[1,0]
	v_exp_f32_e32 v48, v48
	v_exp_f32_e32 v49, v49
	v_exp_f32_e32 v50, v50
	v_exp_f32_e32 v51, v51
	v_exp_f32_e32 v52, v52
	v_exp_f32_e32 v53, v53
	v_exp_f32_e32 v54, v54
	v_exp_f32_e32 v55, v55
	v_pk_add_f32 v[48:49], v[48:49], 1.0 op_sel_hi:[1,0]
	v_pk_add_f32 v[50:51], v[50:51], 1.0 op_sel_hi:[1,0]
	v_pk_add_f32 v[52:53], v[52:53], 1.0 op_sel_hi:[1,0]
	v_pk_add_f32 v[54:55], v[54:55], 1.0 op_sel_hi:[1,0]
	v_rcp_f32_e32 v48, v48
	v_rcp_f32_e32 v49, v49
	v_rcp_f32_e32 v50, v50
	v_rcp_f32_e32 v51, v51
	v_rcp_f32_e32 v52, v52
	v_rcp_f32_e32 v54, v54
	v_rcp_f32_e32 v55, v55
	v_rcp_f32_e32 v53, v53
	v_pk_mul_f32 v[46:47], v[46:47], v[50:51]
	v_pk_mul_f32 v[44:45], v[44:45], v[48:49]
	v_pk_mul_f32 v[42:43], v[42:43], v[54:55]
	v_pk_mul_f32 v[40:41], v[40:41], v[52:53]
.LBB0_643:
	v_lshl_add_u64 v[48:49], v[64:65], 0, s[0:1]
	v_cvt_pk_bf16_f32 v44, v44, v45
	v_cvt_pk_bf16_f32 v45, v46, v47
	v_cvt_pk_bf16_f32 v46, v40, v41
	v_cvt_pk_bf16_f32 v47, v42, v43
	s_and_b64 vcc, exec, s[6:7]
	global_store_dwordx4 v[48:49], v[44:47], off
	s_cbranch_vccnz .LBB0_645
	s_mov_b32 s100, 0xbfb8aa3b
	v_pk_mul_f32 v[40:41], v[36:37], s[100:101] op_sel_hi:[1,0]
	v_pk_mul_f32 v[42:43], v[38:39], s[100:101] op_sel_hi:[1,0]
	v_pk_mul_f32 v[44:45], v[32:33], s[100:101] op_sel_hi:[1,0]
	v_pk_mul_f32 v[46:47], v[34:35], s[100:101] op_sel_hi:[1,0]
	v_exp_f32_e32 v40, v40
	v_exp_f32_e32 v41, v41
	v_exp_f32_e32 v42, v42
	v_exp_f32_e32 v43, v43
	v_exp_f32_e32 v44, v44
	v_exp_f32_e32 v45, v45
	v_exp_f32_e32 v46, v46
	v_exp_f32_e32 v47, v47
	v_pk_add_f32 v[40:41], v[40:41], 1.0 op_sel_hi:[1,0]
	v_pk_add_f32 v[42:43], v[42:43], 1.0 op_sel_hi:[1,0]
	v_pk_add_f32 v[44:45], v[44:45], 1.0 op_sel_hi:[1,0]
	v_pk_add_f32 v[46:47], v[46:47], 1.0 op_sel_hi:[1,0]
	v_rcp_f32_e32 v40, v40
	v_rcp_f32_e32 v41, v41
	v_rcp_f32_e32 v42, v42
	v_rcp_f32_e32 v43, v43
	v_rcp_f32_e32 v44, v44
	v_rcp_f32_e32 v46, v46
	v_rcp_f32_e32 v47, v47
	v_rcp_f32_e32 v45, v45
	v_pk_mul_f32 v[38:39], v[38:39], v[42:43]
	v_pk_mul_f32 v[36:37], v[36:37], v[40:41]
	v_pk_mul_f32 v[34:35], v[34:35], v[46:47]
	v_pk_mul_f32 v[32:33], v[32:33], v[44:45]
.LBB0_645:
	s_mov_b32 s59, s1
	v_cvt_pk_bf16_f32 v36, v36, v37
	v_cvt_pk_bf16_f32 v37, v38, v39
	v_cvt_pk_bf16_f32 v38, v32, v33
	v_cvt_pk_bf16_f32 v39, v34, v35
	v_lshl_add_u64 v[32:33], v[48:49], 0, s[58:59]
	s_and_b64 vcc, exec, s[6:7]
	global_store_dwordx4 v[32:33], v[36:39], off
	s_cbranch_vccnz .LBB0_647
	s_mov_b32 s100, 0xbfb8aa3b
	v_pk_mul_f32 v[32:33], v[28:29], s[100:101] op_sel_hi:[1,0]
	v_pk_mul_f32 v[34:35], v[30:31], s[100:101] op_sel_hi:[1,0]
	v_pk_mul_f32 v[36:37], v[24:25], s[100:101] op_sel_hi:[1,0]
	v_pk_mul_f32 v[38:39], v[26:27], s[100:101] op_sel_hi:[1,0]
	v_exp_f32_e32 v32, v32
	v_exp_f32_e32 v33, v33
	v_exp_f32_e32 v34, v34
	v_exp_f32_e32 v35, v35
	v_exp_f32_e32 v36, v36
	v_exp_f32_e32 v37, v37
	v_exp_f32_e32 v38, v38
	v_exp_f32_e32 v39, v39
	v_pk_add_f32 v[32:33], v[32:33], 1.0 op_sel_hi:[1,0]
	v_pk_add_f32 v[34:35], v[34:35], 1.0 op_sel_hi:[1,0]
	v_pk_add_f32 v[36:37], v[36:37], 1.0 op_sel_hi:[1,0]
	v_pk_add_f32 v[38:39], v[38:39], 1.0 op_sel_hi:[1,0]
	v_rcp_f32_e32 v32, v32
	v_rcp_f32_e32 v33, v33
	v_rcp_f32_e32 v34, v34
	v_rcp_f32_e32 v35, v35
	v_rcp_f32_e32 v36, v36
	v_rcp_f32_e32 v38, v38
	v_rcp_f32_e32 v39, v39
	v_rcp_f32_e32 v37, v37
	v_pk_mul_f32 v[30:31], v[30:31], v[34:35]
	v_pk_mul_f32 v[28:29], v[28:29], v[32:33]
	v_pk_mul_f32 v[26:27], v[26:27], v[38:39]
	v_pk_mul_f32 v[24:25], v[24:25], v[36:37]
.LBB0_647:
	v_lshl_add_u64 v[32:33], v[48:49], 0, s[0:1]
	v_cvt_pk_bf16_f32 v28, v28, v29
	v_cvt_pk_bf16_f32 v29, v30, v31
	v_cvt_pk_bf16_f32 v30, v24, v25
	v_cvt_pk_bf16_f32 v31, v26, v27
	s_and_b64 vcc, exec, s[6:7]
	global_store_dwordx4 v[32:33], v[28:31], off
	s_cbranch_vccnz .LBB0_649
	s_mov_b32 s100, 0xbfb8aa3b
	v_pk_mul_f32 v[24:25], v[20:21], s[100:101] op_sel_hi:[1,0]
	v_pk_mul_f32 v[26:27], v[22:23], s[100:101] op_sel_hi:[1,0]
	v_pk_mul_f32 v[28:29], v[16:17], s[100:101] op_sel_hi:[1,0]
	v_pk_mul_f32 v[30:31], v[18:19], s[100:101] op_sel_hi:[1,0]
	v_exp_f32_e32 v24, v24
	v_exp_f32_e32 v25, v25
	v_exp_f32_e32 v26, v26
	v_exp_f32_e32 v27, v27
	v_exp_f32_e32 v28, v28
	v_exp_f32_e32 v29, v29
	v_exp_f32_e32 v30, v30
	v_exp_f32_e32 v31, v31
	v_pk_add_f32 v[24:25], v[24:25], 1.0 op_sel_hi:[1,0]
	v_pk_add_f32 v[26:27], v[26:27], 1.0 op_sel_hi:[1,0]
	v_pk_add_f32 v[28:29], v[28:29], 1.0 op_sel_hi:[1,0]
	v_pk_add_f32 v[30:31], v[30:31], 1.0 op_sel_hi:[1,0]
	v_rcp_f32_e32 v24, v24
	v_rcp_f32_e32 v25, v25
	v_rcp_f32_e32 v26, v26
	v_rcp_f32_e32 v27, v27
	v_rcp_f32_e32 v28, v28
	v_rcp_f32_e32 v30, v30
	v_rcp_f32_e32 v31, v31
	v_rcp_f32_e32 v29, v29
	v_pk_mul_f32 v[22:23], v[22:23], v[26:27]
	v_pk_mul_f32 v[20:21], v[20:21], v[24:25]
	v_pk_mul_f32 v[18:19], v[18:19], v[30:31]
	v_pk_mul_f32 v[16:17], v[16:17], v[28:29]
.LBB0_649:
	s_mov_b32 s59, s1
	v_cvt_pk_bf16_f32 v20, v20, v21
	v_cvt_pk_bf16_f32 v21, v22, v23
	v_cvt_pk_bf16_f32 v22, v16, v17
	v_cvt_pk_bf16_f32 v23, v18, v19
	v_lshl_add_u64 v[16:17], v[32:33], 0, s[58:59]
	s_and_b64 vcc, exec, s[6:7]
	global_store_dwordx4 v[16:17], v[20:23], off
	s_cbranch_vccnz .LBB0_651
	s_mov_b32 s100, 0xbfb8aa3b
	v_pk_mul_f32 v[16:17], v[12:13], s[100:101] op_sel_hi:[1,0]
	v_pk_mul_f32 v[18:19], v[14:15], s[100:101] op_sel_hi:[1,0]
	v_pk_mul_f32 v[20:21], v[8:9], s[100:101] op_sel_hi:[1,0]
	v_pk_mul_f32 v[22:23], v[10:11], s[100:101] op_sel_hi:[1,0]
	v_exp_f32_e32 v16, v16
	v_exp_f32_e32 v17, v17
	v_exp_f32_e32 v18, v18
	v_exp_f32_e32 v19, v19
	v_exp_f32_e32 v20, v20
	v_exp_f32_e32 v21, v21
	v_exp_f32_e32 v22, v22
	v_exp_f32_e32 v23, v23
	v_pk_add_f32 v[16:17], v[16:17], 1.0 op_sel_hi:[1,0]
	v_pk_add_f32 v[18:19], v[18:19], 1.0 op_sel_hi:[1,0]
	v_pk_add_f32 v[20:21], v[20:21], 1.0 op_sel_hi:[1,0]
	v_pk_add_f32 v[22:23], v[22:23], 1.0 op_sel_hi:[1,0]
	v_rcp_f32_e32 v16, v16
	v_rcp_f32_e32 v17, v17
	v_rcp_f32_e32 v18, v18
	v_rcp_f32_e32 v19, v19
	v_rcp_f32_e32 v20, v20
	v_rcp_f32_e32 v22, v22
	v_rcp_f32_e32 v23, v23
	v_rcp_f32_e32 v21, v21
	v_pk_mul_f32 v[14:15], v[14:15], v[18:19]
	v_pk_mul_f32 v[12:13], v[12:13], v[16:17]
	v_pk_mul_f32 v[10:11], v[10:11], v[22:23]
	v_pk_mul_f32 v[8:9], v[8:9], v[20:21]
.LBB0_651:
	v_lshl_add_u64 v[16:17], v[32:33], 0, s[0:1]
	v_cvt_pk_bf16_f32 v12, v12, v13
	v_cvt_pk_bf16_f32 v13, v14, v15
	v_cvt_pk_bf16_f32 v14, v8, v9
	v_cvt_pk_bf16_f32 v15, v10, v11
	s_and_b64 vcc, exec, s[6:7]
	global_store_dwordx4 v[16:17], v[12:15], off
	s_cbranch_vccnz .LBB0_608
	s_mov_b32 s100, 0xbfb8aa3b
	v_pk_mul_f32 v[8:9], v[4:5], s[100:101] op_sel_hi:[1,0]
	v_pk_mul_f32 v[10:11], v[6:7], s[100:101] op_sel_hi:[1,0]
	v_pk_mul_f32 v[12:13], v[0:1], s[100:101] op_sel_hi:[1,0]
	v_pk_mul_f32 v[14:15], v[2:3], s[100:101] op_sel_hi:[1,0]
	v_exp_f32_e32 v8, v8
	v_exp_f32_e32 v9, v9
	v_exp_f32_e32 v10, v10
	v_exp_f32_e32 v11, v11
	v_exp_f32_e32 v12, v12
	v_exp_f32_e32 v13, v13
	v_exp_f32_e32 v14, v14
	v_exp_f32_e32 v15, v15
	v_pk_add_f32 v[8:9], v[8:9], 1.0 op_sel_hi:[1,0]
	v_pk_add_f32 v[10:11], v[10:11], 1.0 op_sel_hi:[1,0]
	v_pk_add_f32 v[12:13], v[12:13], 1.0 op_sel_hi:[1,0]
	v_pk_add_f32 v[14:15], v[14:15], 1.0 op_sel_hi:[1,0]
	v_rcp_f32_e32 v8, v8
	v_rcp_f32_e32 v9, v9
	v_rcp_f32_e32 v10, v10
	v_rcp_f32_e32 v11, v11
	v_rcp_f32_e32 v12, v12
	v_rcp_f32_e32 v14, v14
	v_rcp_f32_e32 v15, v15
	v_rcp_f32_e32 v13, v13
	v_pk_mul_f32 v[6:7], v[6:7], v[10:11]
	v_pk_mul_f32 v[4:5], v[4:5], v[8:9]
	v_pk_mul_f32 v[2:3], v[2:3], v[14:15]
	v_pk_mul_f32 v[0:1], v[0:1], v[12:13]
	s_branch .LBB0_608
